# stack + the eight GEMM K-loop heads and the MoBA group loop head aligned to 64 bytes
# baseline (speedup 1.0000x reference)
.LBB0_135:
	s_ashr_i32 s71, s70, 31
	s_lshl_b64 s[44:45], s[70:71], 19
	s_add_u32 s72, s4, s44
	s_addc_u32 s73, s5, s45
	s_and_b64 s[44:45], s[38:39], exec
	s_cselect_b32 s1, s73, s79
	s_cselect_b32 s71, s72, s78
	s_ashr_i32 s69, s68, 31
	s_lshl_b64 s[44:45], s[68:69], 19
	s_add_u32 s74, s56, s44
	s_addc_u32 s75, s57, s45
	s_and_b64 s[44:45], s[38:39], exec
	s_cselect_b32 s69, s75, s3
	s_cselect_b32 vcc_lo, s74, s2
	s_add_u32 s78, s78, 0x40080
	s_addc_u32 s79, s79, 0
	s_add_u32 vcc_hi, s2, 0x100
	v_mov_b32_e32 v4, 0
	s_addc_u32 s44, s3, 0
	s_mov_b32 s45, -2
	v_mov_b32_e32 v5, v4
	v_mov_b32_e32 v6, v4
	v_mov_b32_e32 v7, v4
	v_mov_b32_e32 v8, v4
	v_mov_b32_e32 v9, v4
	v_mov_b32_e32 v10, v4
	v_mov_b32_e32 v11, v4
	v_mov_b32_e32 v20, v4
	v_mov_b32_e32 v21, v4
	v_mov_b32_e32 v22, v4
	v_mov_b32_e32 v23, v4
	v_mov_b32_e32 v24, v4
	v_mov_b32_e32 v25, v4
	v_mov_b32_e32 v26, v4
	v_mov_b32_e32 v27, v4
	v_mov_b32_e32 v36, v4
	v_mov_b32_e32 v37, v4
	v_mov_b32_e32 v38, v4
	v_mov_b32_e32 v39, v4
	v_mov_b32_e32 v40, v4
	v_mov_b32_e32 v41, v4
	v_mov_b32_e32 v42, v4
	v_mov_b32_e32 v43, v4
	v_mov_b32_e32 v52, v4
	v_mov_b32_e32 v53, v4
	v_mov_b32_e32 v54, v4
	v_mov_b32_e32 v55, v4
	v_mov_b32_e32 v56, v4
	v_mov_b32_e32 v57, v4
	v_mov_b32_e32 v58, v4
	v_mov_b32_e32 v59, v4
	v_mov_b32_e32 v12, v4
	v_mov_b32_e32 v13, v4
	v_mov_b32_e32 v14, v4
	v_mov_b32_e32 v15, v4
	v_mov_b32_e32 v16, v4
	v_mov_b32_e32 v17, v4
	v_mov_b32_e32 v18, v4
	v_mov_b32_e32 v19, v4
	v_mov_b32_e32 v28, v4
	v_mov_b32_e32 v29, v4
	v_mov_b32_e32 v30, v4
	v_mov_b32_e32 v31, v4
	v_mov_b32_e32 v32, v4
	v_mov_b32_e32 v33, v4
	v_mov_b32_e32 v34, v4
	v_mov_b32_e32 v35, v4
	v_mov_b32_e32 v44, v4
	v_mov_b32_e32 v45, v4
	v_mov_b32_e32 v46, v4
	v_mov_b32_e32 v47, v4
	v_mov_b32_e32 v48, v4
	v_mov_b32_e32 v49, v4
	v_mov_b32_e32 v50, v4
	v_mov_b32_e32 v51, v4
	v_mov_b32_e32 v60, v4
	v_mov_b32_e32 v61, v4
	v_mov_b32_e32 v62, v4
	v_mov_b32_e32 v63, v4
	v_mov_b32_e32 v64, v4
	v_mov_b32_e32 v65, v4
	v_mov_b32_e32 v66, v4
	v_mov_b32_e32 v67, v4
	v_mov_b32_e32 v68, v4
	v_mov_b32_e32 v69, v4
	v_mov_b32_e32 v70, v4
	v_mov_b32_e32 v71, v4
	v_mov_b32_e32 v72, v4
	v_mov_b32_e32 v73, v4
	v_mov_b32_e32 v74, v4
	v_mov_b32_e32 v75, v4
	v_mov_b32_e32 v88, v4
	v_mov_b32_e32 v89, v4
	v_mov_b32_e32 v90, v4
	v_mov_b32_e32 v91, v4
	v_mov_b32_e32 v92, v4
	v_mov_b32_e32 v93, v4
	v_mov_b32_e32 v94, v4
	v_mov_b32_e32 v95, v4
	v_mov_b32_e32 v108, v4
	v_mov_b32_e32 v109, v4
	v_mov_b32_e32 v110, v4
	v_mov_b32_e32 v111, v4
	v_mov_b32_e32 v112, v4
	v_mov_b32_e32 v113, v4
	v_mov_b32_e32 v114, v4
	v_mov_b32_e32 v115, v4
	v_mov_b32_e32 v84, v4
	v_mov_b32_e32 v85, v4
	v_mov_b32_e32 v86, v4
	v_mov_b32_e32 v87, v4
	v_mov_b32_e32 v104, v4
	v_mov_b32_e32 v105, v4
	v_mov_b32_e32 v106, v4
	v_mov_b32_e32 v107, v4
	v_mov_b32_e32 v76, v4
	v_mov_b32_e32 v77, v4
	v_mov_b32_e32 v78, v4
	v_mov_b32_e32 v79, v4
	v_mov_b32_e32 v80, v4
	v_mov_b32_e32 v81, v4
	v_mov_b32_e32 v82, v4
	v_mov_b32_e32 v83, v4
	v_mov_b32_e32 v96, v4
	v_mov_b32_e32 v97, v4
	v_mov_b32_e32 v98, v4
	v_mov_b32_e32 v99, v4
	v_mov_b32_e32 v100, v4
	v_mov_b32_e32 v101, v4
	v_mov_b32_e32 v102, v4
	v_mov_b32_e32 v103, v4
	v_mov_b32_e32 v116, v4
	v_mov_b32_e32 v117, v4
	v_mov_b32_e32 v118, v4
	v_mov_b32_e32 v119, v4
	v_mov_b32_e32 v120, v4
	v_mov_b32_e32 v121, v4
	v_mov_b32_e32 v122, v4
	v_mov_b32_e32 v123, v4
	v_mov_b32_e32 v124, v4
	v_mov_b32_e32 v125, v4
	v_mov_b32_e32 v126, v4
	v_mov_b32_e32 v127, v4
	v_mov_b32_e32 v128, v4
	v_mov_b32_e32 v129, v4
	v_mov_b32_e32 v130, v4
	v_mov_b32_e32 v131, v4
	.p2align 6

.LBB0_385:
	s_cmp_ge_i32 s89, s42
	s_cbranch_scc1 .LBB0_406
	v_and_b32_e32 v1, 64, v232
	v_xor_b32_e32 v0, 32, v232
	v_add_u32_e32 v2, 64, v1
	v_cmp_lt_i32_e32 vcc, v0, v2
	v_add_u32_e32 v194, s58, v199
	v_add_u32_e32 v187, s8, v199
	v_cndmask_b32_e32 v0, v232, v0, vcc
	v_lshlrev_b32_e32 v238, 2, v0
	v_or_b32_e32 v0, v1, v219
	v_lshlrev_b32_e32 v239, 2, v0
	s_mov_b64 s[80:81], -1
	v_mov_b32_e32 v196, 3
	v_mov_b32_e32 v240, v171
	v_mov_b32_e32 v241, v202
	s_mov_b32 s58, s89
	.p2align 6

.LBB0_537:
	s_ashr_i32 s41, s40, 31
	s_lshl_b64 s[42:43], s[40:41], 19
	s_add_u32 s42, s24, s42
	s_addc_u32 s43, s25, s43
	s_and_b64 s[44:45], s[0:1], exec
	s_cselect_b32 s41, s43, s49
	s_cselect_b32 s60, s42, s48
	s_ashr_i32 s39, s38, 31
	s_lshl_b64 s[44:45], s[38:39], 19
	s_add_u32 s44, s94, s44
	s_addc_u32 s45, s95, s45
	s_and_b64 s[50:51], s[0:1], exec
	s_cselect_b32 s39, s45, s3
	s_cselect_b32 s61, s44, s2
	s_add_u32 s48, s48, 0x40080
	s_addc_u32 s49, s49, 0
	s_add_u32 s62, s2, 0x100
	v_mov_b32_e32 v0, 0
	s_addc_u32 s63, s3, 0
	s_mov_b32 s64, -2
	v_mov_b32_e32 v1, v0
	v_mov_b32_e32 v2, v0
	v_mov_b32_e32 v3, v0
	v_mov_b32_e32 v4, v0
	v_mov_b32_e32 v5, v0
	v_mov_b32_e32 v6, v0
	v_mov_b32_e32 v7, v0
	v_mov_b32_e32 v16, v0
	v_mov_b32_e32 v17, v0
	v_mov_b32_e32 v18, v0
	v_mov_b32_e32 v19, v0
	v_mov_b32_e32 v20, v0
	v_mov_b32_e32 v21, v0
	v_mov_b32_e32 v22, v0
	v_mov_b32_e32 v23, v0
	v_mov_b32_e32 v32, v0
	v_mov_b32_e32 v33, v0
	v_mov_b32_e32 v34, v0
	v_mov_b32_e32 v35, v0
	v_mov_b32_e32 v36, v0
	v_mov_b32_e32 v37, v0
	v_mov_b32_e32 v38, v0
	v_mov_b32_e32 v39, v0
	v_mov_b32_e32 v48, v0
	v_mov_b32_e32 v49, v0
	v_mov_b32_e32 v50, v0
	v_mov_b32_e32 v51, v0
	v_mov_b32_e32 v52, v0
	v_mov_b32_e32 v53, v0
	v_mov_b32_e32 v54, v0
	v_mov_b32_e32 v55, v0
	v_mov_b32_e32 v8, v0
	v_mov_b32_e32 v9, v0
	v_mov_b32_e32 v10, v0
	v_mov_b32_e32 v11, v0
	v_mov_b32_e32 v12, v0
	v_mov_b32_e32 v13, v0
	v_mov_b32_e32 v14, v0
	v_mov_b32_e32 v15, v0
	v_mov_b32_e32 v24, v0
	v_mov_b32_e32 v25, v0
	v_mov_b32_e32 v26, v0
	v_mov_b32_e32 v27, v0
	v_mov_b32_e32 v28, v0
	v_mov_b32_e32 v29, v0
	v_mov_b32_e32 v30, v0
	v_mov_b32_e32 v31, v0
	v_mov_b32_e32 v40, v0
	v_mov_b32_e32 v41, v0
	v_mov_b32_e32 v42, v0
	v_mov_b32_e32 v43, v0
	v_mov_b32_e32 v44, v0
	v_mov_b32_e32 v45, v0
	v_mov_b32_e32 v46, v0
	v_mov_b32_e32 v47, v0
	v_mov_b32_e32 v56, v0
	v_mov_b32_e32 v57, v0
	v_mov_b32_e32 v58, v0
	v_mov_b32_e32 v59, v0
	v_mov_b32_e32 v60, v0
	v_mov_b32_e32 v61, v0
	v_mov_b32_e32 v62, v0
	v_mov_b32_e32 v63, v0
	s_waitcnt vmcnt(0)
	v_mov_b32_e32 v64, v0
	v_mov_b32_e32 v65, v0
	v_mov_b32_e32 v66, v0
	v_mov_b32_e32 v67, v0
	v_mov_b32_e32 v68, v0
	v_mov_b32_e32 v69, v0
	v_mov_b32_e32 v70, v0
	v_mov_b32_e32 v71, v0
	v_mov_b32_e32 v80, v0
	v_mov_b32_e32 v81, v0
	v_mov_b32_e32 v82, v0
	v_mov_b32_e32 v83, v0
	v_mov_b32_e32 v84, v0
	v_mov_b32_e32 v85, v0
	v_mov_b32_e32 v86, v0
	v_mov_b32_e32 v87, v0
	v_mov_b32_e32 v96, v0
	v_mov_b32_e32 v97, v0
	v_mov_b32_e32 v98, v0
	v_mov_b32_e32 v99, v0
	v_mov_b32_e32 v100, v0
	v_mov_b32_e32 v101, v0
	v_mov_b32_e32 v102, v0
	v_mov_b32_e32 v103, v0
	v_mov_b32_e32 v112, v0
	v_mov_b32_e32 v113, v0
	v_mov_b32_e32 v114, v0
	v_mov_b32_e32 v115, v0
	v_mov_b32_e32 v116, v0
	v_mov_b32_e32 v117, v0
	v_mov_b32_e32 v118, v0
	v_mov_b32_e32 v119, v0
	v_mov_b32_e32 v72, v0
	v_mov_b32_e32 v73, v0
	v_mov_b32_e32 v74, v0
	v_mov_b32_e32 v75, v0
	v_mov_b32_e32 v76, v0
	v_mov_b32_e32 v77, v0
	v_mov_b32_e32 v78, v0
	v_mov_b32_e32 v79, v0
	v_mov_b32_e32 v88, v0
	v_mov_b32_e32 v89, v0
	v_mov_b32_e32 v90, v0
	v_mov_b32_e32 v91, v0
	v_mov_b32_e32 v92, v0
	v_mov_b32_e32 v93, v0
	v_mov_b32_e32 v94, v0
	v_mov_b32_e32 v95, v0
	v_mov_b32_e32 v104, v0
	v_mov_b32_e32 v105, v0
	v_mov_b32_e32 v106, v0
	v_mov_b32_e32 v107, v0
	v_mov_b32_e32 v108, v0
	v_mov_b32_e32 v109, v0
	v_mov_b32_e32 v110, v0
	v_mov_b32_e32 v111, v0
	v_mov_b32_e32 v120, v0
	v_mov_b32_e32 v121, v0
	v_mov_b32_e32 v122, v0
	v_mov_b32_e32 v123, v0
	v_mov_b32_e32 v124, v0
	v_mov_b32_e32 v125, v0
	v_mov_b32_e32 v126, v0
	v_mov_b32_e32 v127, v0
	.p2align 6

.LBB0_610:
	s_ashr_i32 s43, s42, 31
	s_lshl_b64 s[10:11], s[42:43], 19
	s_add_u32 s44, s26, s10
	s_addc_u32 s45, s27, s11
	s_and_b64 s[10:11], s[0:1], exec
	s_cselect_b32 s43, s45, s9
	s_cselect_b32 s59, s44, s8
	s_ashr_i32 s41, s40, 31
	s_lshl_b64 s[10:11], s[40:41], 19
	s_add_u32 s46, s33, s10
	s_addc_u32 s47, s39, s11
	s_and_b64 s[10:11], s[0:1], exec
	s_cselect_b32 s41, s47, s3
	s_cselect_b32 s60, s46, s2
	s_add_u32 s8, s8, 0x40080
	s_addc_u32 s9, s9, 0
	s_add_u32 s61, s2, 0x100
	v_mov_b32_e32 v0, 0
	s_addc_u32 s62, s3, 0
	s_mov_b32 s63, -2
	v_mov_b32_e32 v1, v0
	v_mov_b32_e32 v2, v0
	v_mov_b32_e32 v3, v0
	v_mov_b32_e32 v4, v0
	v_mov_b32_e32 v5, v0
	v_mov_b32_e32 v6, v0
	v_mov_b32_e32 v7, v0
	v_mov_b32_e32 v16, v0
	v_mov_b32_e32 v17, v0
	v_mov_b32_e32 v18, v0
	v_mov_b32_e32 v19, v0
	v_mov_b32_e32 v20, v0
	v_mov_b32_e32 v21, v0
	v_mov_b32_e32 v22, v0
	v_mov_b32_e32 v23, v0
	v_mov_b32_e32 v32, v0
	v_mov_b32_e32 v33, v0
	v_mov_b32_e32 v34, v0
	v_mov_b32_e32 v35, v0
	v_mov_b32_e32 v36, v0
	v_mov_b32_e32 v37, v0
	v_mov_b32_e32 v38, v0
	v_mov_b32_e32 v39, v0
	v_mov_b32_e32 v48, v0
	v_mov_b32_e32 v49, v0
	v_mov_b32_e32 v50, v0
	v_mov_b32_e32 v51, v0
	v_mov_b32_e32 v52, v0
	v_mov_b32_e32 v53, v0
	v_mov_b32_e32 v54, v0
	v_mov_b32_e32 v55, v0
	v_mov_b32_e32 v8, v0
	v_mov_b32_e32 v9, v0
	v_mov_b32_e32 v10, v0
	v_mov_b32_e32 v11, v0
	v_mov_b32_e32 v12, v0
	v_mov_b32_e32 v13, v0
	v_mov_b32_e32 v14, v0
	v_mov_b32_e32 v15, v0
	v_mov_b32_e32 v24, v0
	v_mov_b32_e32 v25, v0
	v_mov_b32_e32 v26, v0
	v_mov_b32_e32 v27, v0
	v_mov_b32_e32 v28, v0
	v_mov_b32_e32 v29, v0
	v_mov_b32_e32 v30, v0
	v_mov_b32_e32 v31, v0
	v_mov_b32_e32 v40, v0
	v_mov_b32_e32 v41, v0
	v_mov_b32_e32 v42, v0
	v_mov_b32_e32 v43, v0
	v_mov_b32_e32 v44, v0
	v_mov_b32_e32 v45, v0
	v_mov_b32_e32 v46, v0
	v_mov_b32_e32 v47, v0
	v_mov_b32_e32 v56, v0
	v_mov_b32_e32 v57, v0
	v_mov_b32_e32 v58, v0
	v_mov_b32_e32 v59, v0
	v_mov_b32_e32 v60, v0
	v_mov_b32_e32 v61, v0
	v_mov_b32_e32 v62, v0
	v_mov_b32_e32 v63, v0
	s_waitcnt vmcnt(0)
	v_mov_b32_e32 v64, v0
	v_mov_b32_e32 v65, v0
	v_mov_b32_e32 v66, v0
	v_mov_b32_e32 v67, v0
	v_mov_b32_e32 v68, v0
	v_mov_b32_e32 v69, v0
	v_mov_b32_e32 v70, v0
	v_mov_b32_e32 v71, v0
	v_mov_b32_e32 v80, v0
	v_mov_b32_e32 v81, v0
	v_mov_b32_e32 v82, v0
	v_mov_b32_e32 v83, v0
	v_mov_b32_e32 v84, v0
	v_mov_b32_e32 v85, v0
	v_mov_b32_e32 v86, v0
	v_mov_b32_e32 v87, v0
	v_mov_b32_e32 v96, v0
	v_mov_b32_e32 v97, v0
	v_mov_b32_e32 v98, v0
	v_mov_b32_e32 v99, v0
	v_mov_b32_e32 v100, v0
	v_mov_b32_e32 v101, v0
	v_mov_b32_e32 v102, v0
	v_mov_b32_e32 v103, v0
	v_mov_b32_e32 v112, v0
	v_mov_b32_e32 v113, v0
	v_mov_b32_e32 v114, v0
	v_mov_b32_e32 v115, v0
	v_mov_b32_e32 v116, v0
	v_mov_b32_e32 v117, v0
	v_mov_b32_e32 v118, v0
	v_mov_b32_e32 v119, v0
	v_mov_b32_e32 v72, v0
	v_mov_b32_e32 v73, v0
	v_mov_b32_e32 v74, v0
	v_mov_b32_e32 v75, v0
	v_mov_b32_e32 v76, v0
	v_mov_b32_e32 v77, v0
	v_mov_b32_e32 v78, v0
	v_mov_b32_e32 v79, v0
	v_mov_b32_e32 v88, v0
	v_mov_b32_e32 v89, v0
	v_mov_b32_e32 v90, v0
	v_mov_b32_e32 v91, v0
	v_mov_b32_e32 v92, v0
	v_mov_b32_e32 v93, v0
	v_mov_b32_e32 v94, v0
	v_mov_b32_e32 v95, v0
	v_mov_b32_e32 v104, v0
	v_mov_b32_e32 v105, v0
	v_mov_b32_e32 v106, v0
	v_mov_b32_e32 v107, v0
	v_mov_b32_e32 v108, v0
	v_mov_b32_e32 v109, v0
	v_mov_b32_e32 v110, v0
	v_mov_b32_e32 v111, v0
	v_mov_b32_e32 v120, v0
	v_mov_b32_e32 v121, v0
	v_mov_b32_e32 v122, v0
	v_mov_b32_e32 v123, v0
	v_mov_b32_e32 v124, v0
	v_mov_b32_e32 v125, v0
	v_mov_b32_e32 v126, v0
	v_mov_b32_e32 v127, v0
	.p2align 6

.LBB0_683:
	s_ashr_i32 s45, s44, 31
	s_lshl_b64 s[46:47], s[44:45], 21
	s_add_u32 s46, s24, s46
	s_addc_u32 s47, s25, s47
	s_and_b64 s[48:49], s[8:9], exec
	s_cselect_b32 s45, s47, s51
	s_cselect_b32 s64, s46, s50
	s_ashr_i32 s43, s42, 31
	s_lshl_b64 s[48:49], s[42:43], 21
	s_add_u32 s48, s33, s48
	s_addc_u32 s49, s39, s49
	s_and_b64 s[52:53], s[8:9], exec
	s_cselect_b32 s43, s49, s3
	s_cselect_b32 s65, s48, s2
	s_add_u32 s50, s50, 0x100080
	s_addc_u32 s51, s51, 0
	s_add_u32 s66, s2, 0x100
	v_mov_b32_e32 v0, 0
	s_addc_u32 s67, s3, 0
	s_mov_b32 s68, -2
	v_mov_b32_e32 v1, v0
	v_mov_b32_e32 v2, v0
	v_mov_b32_e32 v3, v0
	v_mov_b32_e32 v4, v0
	v_mov_b32_e32 v5, v0
	v_mov_b32_e32 v6, v0
	v_mov_b32_e32 v7, v0
	v_mov_b32_e32 v16, v0
	v_mov_b32_e32 v17, v0
	v_mov_b32_e32 v18, v0
	v_mov_b32_e32 v19, v0
	v_mov_b32_e32 v20, v0
	v_mov_b32_e32 v21, v0
	v_mov_b32_e32 v22, v0
	v_mov_b32_e32 v23, v0
	v_mov_b32_e32 v32, v0
	v_mov_b32_e32 v33, v0
	v_mov_b32_e32 v34, v0
	v_mov_b32_e32 v35, v0
	v_mov_b32_e32 v36, v0
	v_mov_b32_e32 v37, v0
	v_mov_b32_e32 v38, v0
	v_mov_b32_e32 v39, v0
	v_mov_b32_e32 v48, v0
	v_mov_b32_e32 v49, v0
	v_mov_b32_e32 v50, v0
	v_mov_b32_e32 v51, v0
	v_mov_b32_e32 v52, v0
	v_mov_b32_e32 v53, v0
	v_mov_b32_e32 v54, v0
	v_mov_b32_e32 v55, v0
	v_mov_b32_e32 v8, v0
	v_mov_b32_e32 v9, v0
	v_mov_b32_e32 v10, v0
	v_mov_b32_e32 v11, v0
	v_mov_b32_e32 v12, v0
	v_mov_b32_e32 v13, v0
	v_mov_b32_e32 v14, v0
	v_mov_b32_e32 v15, v0
	v_mov_b32_e32 v24, v0
	v_mov_b32_e32 v25, v0
	v_mov_b32_e32 v26, v0
	v_mov_b32_e32 v27, v0
	v_mov_b32_e32 v28, v0
	v_mov_b32_e32 v29, v0
	v_mov_b32_e32 v30, v0
	v_mov_b32_e32 v31, v0
	v_mov_b32_e32 v40, v0
	v_mov_b32_e32 v41, v0
	v_mov_b32_e32 v42, v0
	v_mov_b32_e32 v43, v0
	v_mov_b32_e32 v44, v0
	v_mov_b32_e32 v45, v0
	v_mov_b32_e32 v46, v0
	v_mov_b32_e32 v47, v0
	v_mov_b32_e32 v56, v0
	v_mov_b32_e32 v57, v0
	v_mov_b32_e32 v58, v0
	v_mov_b32_e32 v59, v0
	v_mov_b32_e32 v60, v0
	v_mov_b32_e32 v61, v0
	v_mov_b32_e32 v62, v0
	v_mov_b32_e32 v63, v0
	v_mov_b32_e32 v80, v0
	v_mov_b32_e32 v81, v0
	v_mov_b32_e32 v82, v0
	v_mov_b32_e32 v83, v0
	v_mov_b32_e32 v84, v0
	v_mov_b32_e32 v85, v0
	v_mov_b32_e32 v86, v0
	v_mov_b32_e32 v87, v0
	v_mov_b32_e32 v112, v0
	v_mov_b32_e32 v113, v0
	v_mov_b32_e32 v114, v0
	v_mov_b32_e32 v115, v0
	v_mov_b32_e32 v116, v0
	v_mov_b32_e32 v117, v0
	v_mov_b32_e32 v118, v0
	v_mov_b32_e32 v119, v0
	v_mov_b32_e32 v128, v0
	v_mov_b32_e32 v129, v0
	v_mov_b32_e32 v130, v0
	v_mov_b32_e32 v131, v0
	v_mov_b32_e32 v132, v0
	v_mov_b32_e32 v133, v0
	v_mov_b32_e32 v134, v0
	v_mov_b32_e32 v135, v0
	v_mov_b32_e32 v144, v0
	v_mov_b32_e32 v145, v0
	v_mov_b32_e32 v146, v0
	v_mov_b32_e32 v147, v0
	v_mov_b32_e32 v148, v0
	v_mov_b32_e32 v149, v0
	v_mov_b32_e32 v150, v0
	v_mov_b32_e32 v151, v0
	v_mov_b32_e32 v104, v0
	v_mov_b32_e32 v105, v0
	v_mov_b32_e32 v106, v0
	v_mov_b32_e32 v107, v0
	v_mov_b32_e32 v108, v0
	v_mov_b32_e32 v109, v0
	v_mov_b32_e32 v110, v0
	v_mov_b32_e32 v111, v0
	v_mov_b32_e32 v120, v0
	v_mov_b32_e32 v121, v0
	v_mov_b32_e32 v122, v0
	v_mov_b32_e32 v123, v0
	v_mov_b32_e32 v124, v0
	v_mov_b32_e32 v125, v0
	v_mov_b32_e32 v126, v0
	v_mov_b32_e32 v127, v0
	v_mov_b32_e32 v136, v0
	v_mov_b32_e32 v137, v0
	v_mov_b32_e32 v138, v0
	v_mov_b32_e32 v139, v0
	v_mov_b32_e32 v140, v0
	v_mov_b32_e32 v141, v0
	v_mov_b32_e32 v142, v0
	v_mov_b32_e32 v143, v0
	v_mov_b32_e32 v152, v0
	v_mov_b32_e32 v153, v0
	v_mov_b32_e32 v154, v0
	v_mov_b32_e32 v155, v0
	v_mov_b32_e32 v156, v0
	v_mov_b32_e32 v157, v0
	v_mov_b32_e32 v158, v0
	v_mov_b32_e32 v159, v0
	.p2align 6

.LBB0_752:
	s_ashr_i32 s45, s44, 31
	s_lshl_b64 s[46:47], s[44:45], 19
	s_add_u32 s46, s26, s46
	s_addc_u32 s47, s27, s47
	s_and_b64 s[48:49], s[6:7], exec
	s_cselect_b32 s1, s47, s51
	s_cselect_b32 s45, s46, s50
	s_ashr_i32 s43, s42, 31
	s_lshl_b64 s[48:49], s[42:43], 19
	v_readlane_b32 s52, v251, 22
	v_readlane_b32 s53, v251, 23
	s_add_u32 s48, s52, s48
	s_addc_u32 s49, s53, s49
	s_and_b64 s[52:53], s[6:7], exec
	s_cselect_b32 s43, s49, s3
	s_cselect_b32 s84, s48, s2
	s_add_u32 s50, s50, 0x40080
	s_addc_u32 s51, s51, 0
	s_add_u32 s85, s2, 0x100
	v_mov_b32_e32 v0, 0
	s_addc_u32 s86, s3, 0
	s_mov_b32 s87, -2
	v_mov_b32_e32 v1, v0
	v_mov_b32_e32 v2, v0
	v_mov_b32_e32 v3, v0
	v_mov_b32_e32 v4, v0
	v_mov_b32_e32 v5, v0
	v_mov_b32_e32 v6, v0
	v_mov_b32_e32 v7, v0
	v_mov_b32_e32 v16, v0
	v_mov_b32_e32 v17, v0
	v_mov_b32_e32 v18, v0
	v_mov_b32_e32 v19, v0
	v_mov_b32_e32 v20, v0
	v_mov_b32_e32 v21, v0
	v_mov_b32_e32 v22, v0
	v_mov_b32_e32 v23, v0
	v_mov_b32_e32 v32, v0
	v_mov_b32_e32 v33, v0
	v_mov_b32_e32 v34, v0
	v_mov_b32_e32 v35, v0
	v_mov_b32_e32 v36, v0
	v_mov_b32_e32 v37, v0
	v_mov_b32_e32 v38, v0
	v_mov_b32_e32 v39, v0
	v_mov_b32_e32 v48, v0
	v_mov_b32_e32 v49, v0
	v_mov_b32_e32 v50, v0
	v_mov_b32_e32 v51, v0
	v_mov_b32_e32 v52, v0
	v_mov_b32_e32 v53, v0
	v_mov_b32_e32 v54, v0
	v_mov_b32_e32 v55, v0
	v_mov_b32_e32 v8, v0
	v_mov_b32_e32 v9, v0
	v_mov_b32_e32 v10, v0
	v_mov_b32_e32 v11, v0
	v_mov_b32_e32 v12, v0
	v_mov_b32_e32 v13, v0
	v_mov_b32_e32 v14, v0
	v_mov_b32_e32 v15, v0
	v_mov_b32_e32 v24, v0
	v_mov_b32_e32 v25, v0
	v_mov_b32_e32 v26, v0
	v_mov_b32_e32 v27, v0
	v_mov_b32_e32 v28, v0
	v_mov_b32_e32 v29, v0
	v_mov_b32_e32 v30, v0
	v_mov_b32_e32 v31, v0
	v_mov_b32_e32 v40, v0
	v_mov_b32_e32 v41, v0
	v_mov_b32_e32 v42, v0
	v_mov_b32_e32 v43, v0
	v_mov_b32_e32 v44, v0
	v_mov_b32_e32 v45, v0
	v_mov_b32_e32 v46, v0
	v_mov_b32_e32 v47, v0
	v_mov_b32_e32 v56, v0
	v_mov_b32_e32 v57, v0
	v_mov_b32_e32 v58, v0
	v_mov_b32_e32 v59, v0
	v_mov_b32_e32 v60, v0
	v_mov_b32_e32 v61, v0
	v_mov_b32_e32 v62, v0
	v_mov_b32_e32 v63, v0
	s_waitcnt vmcnt(0)
	v_mov_b32_e32 v64, v0
	v_mov_b32_e32 v65, v0
	v_mov_b32_e32 v66, v0
	v_mov_b32_e32 v67, v0
	v_mov_b32_e32 v68, v0
	v_mov_b32_e32 v69, v0
	v_mov_b32_e32 v70, v0
	v_mov_b32_e32 v71, v0
	v_mov_b32_e32 v80, v0
	v_mov_b32_e32 v81, v0
	v_mov_b32_e32 v82, v0
	v_mov_b32_e32 v83, v0
	v_mov_b32_e32 v84, v0
	v_mov_b32_e32 v85, v0
	v_mov_b32_e32 v86, v0
	v_mov_b32_e32 v87, v0
	v_mov_b32_e32 v128, v0
	v_mov_b32_e32 v129, v0
	v_mov_b32_e32 v130, v0
	v_mov_b32_e32 v131, v0
	v_mov_b32_e32 v132, v0
	v_mov_b32_e32 v133, v0
	v_mov_b32_e32 v134, v0
	v_mov_b32_e32 v135, v0
	v_mov_b32_e32 v144, v0
	v_mov_b32_e32 v145, v0
	v_mov_b32_e32 v146, v0
	v_mov_b32_e32 v147, v0
	v_mov_b32_e32 v148, v0
	v_mov_b32_e32 v149, v0
	v_mov_b32_e32 v150, v0
	v_mov_b32_e32 v151, v0
	v_mov_b32_e32 v72, v0
	v_mov_b32_e32 v73, v0
	v_mov_b32_e32 v74, v0
	v_mov_b32_e32 v75, v0
	v_mov_b32_e32 v76, v0
	v_mov_b32_e32 v77, v0
	v_mov_b32_e32 v78, v0
	v_mov_b32_e32 v79, v0
	v_mov_b32_e32 v88, v0
	v_mov_b32_e32 v89, v0
	v_mov_b32_e32 v90, v0
	v_mov_b32_e32 v91, v0
	v_mov_b32_e32 v92, v0
	v_mov_b32_e32 v93, v0
	v_mov_b32_e32 v94, v0
	v_mov_b32_e32 v95, v0
	v_mov_b32_e32 v136, v0
	v_mov_b32_e32 v137, v0
	v_mov_b32_e32 v138, v0
	v_mov_b32_e32 v139, v0
	v_mov_b32_e32 v140, v0
	v_mov_b32_e32 v141, v0
	v_mov_b32_e32 v142, v0
	v_mov_b32_e32 v143, v0
	v_mov_b32_e32 v152, v0
	v_mov_b32_e32 v153, v0
	v_mov_b32_e32 v154, v0
	v_mov_b32_e32 v155, v0
	v_mov_b32_e32 v156, v0
	v_mov_b32_e32 v157, v0
	v_mov_b32_e32 v158, v0
	v_mov_b32_e32 v159, v0
	.p2align 6

.LBB0_1009:
	s_add_u32 s60, s2, 0x100
	v_mov_b32_e32 v0, 0
	s_addc_u32 s61, s3, 0
	s_mov_b32 s62, -2
	v_mov_b32_e32 v1, v0
	v_mov_b32_e32 v2, v0
	v_mov_b32_e32 v3, v0
	v_mov_b32_e32 v4, v0
	v_mov_b32_e32 v5, v0
	v_mov_b32_e32 v6, v0
	v_mov_b32_e32 v7, v0
	v_mov_b32_e32 v16, v0
	v_mov_b32_e32 v17, v0
	v_mov_b32_e32 v18, v0
	v_mov_b32_e32 v19, v0
	v_mov_b32_e32 v20, v0
	v_mov_b32_e32 v21, v0
	v_mov_b32_e32 v22, v0
	v_mov_b32_e32 v23, v0
	v_mov_b32_e32 v32, v0
	v_mov_b32_e32 v33, v0
	v_mov_b32_e32 v34, v0
	v_mov_b32_e32 v35, v0
	v_mov_b32_e32 v36, v0
	v_mov_b32_e32 v37, v0
	v_mov_b32_e32 v38, v0
	v_mov_b32_e32 v39, v0
	v_mov_b32_e32 v48, v0
	v_mov_b32_e32 v49, v0
	v_mov_b32_e32 v50, v0
	v_mov_b32_e32 v51, v0
	v_mov_b32_e32 v52, v0
	v_mov_b32_e32 v53, v0
	v_mov_b32_e32 v54, v0
	v_mov_b32_e32 v55, v0
	v_mov_b32_e32 v8, v0
	v_mov_b32_e32 v9, v0
	v_mov_b32_e32 v10, v0
	v_mov_b32_e32 v11, v0
	v_mov_b32_e32 v12, v0
	v_mov_b32_e32 v13, v0
	v_mov_b32_e32 v14, v0
	v_mov_b32_e32 v15, v0
	v_mov_b32_e32 v24, v0
	v_mov_b32_e32 v25, v0
	v_mov_b32_e32 v26, v0
	v_mov_b32_e32 v27, v0
	v_mov_b32_e32 v28, v0
	v_mov_b32_e32 v29, v0
	v_mov_b32_e32 v30, v0
	v_mov_b32_e32 v31, v0
	v_mov_b32_e32 v40, v0
	v_mov_b32_e32 v41, v0
	v_mov_b32_e32 v42, v0
	v_mov_b32_e32 v43, v0
	v_mov_b32_e32 v44, v0
	v_mov_b32_e32 v45, v0
	v_mov_b32_e32 v46, v0
	v_mov_b32_e32 v47, v0
	v_mov_b32_e32 v56, v0
	v_mov_b32_e32 v57, v0
	v_mov_b32_e32 v58, v0
	v_mov_b32_e32 v59, v0
	v_mov_b32_e32 v60, v0
	v_mov_b32_e32 v61, v0
	v_mov_b32_e32 v62, v0
	v_mov_b32_e32 v63, v0
	s_waitcnt vmcnt(0)
	v_mov_b32_e32 v80, v0
	v_mov_b32_e32 v81, v0
	v_mov_b32_e32 v82, v0
	v_mov_b32_e32 v83, v0
	v_mov_b32_e32 v84, v0
	v_mov_b32_e32 v85, v0
	v_mov_b32_e32 v86, v0
	v_mov_b32_e32 v87, v0
	v_mov_b32_e32 v112, v0
	v_mov_b32_e32 v113, v0
	v_mov_b32_e32 v114, v0
	v_mov_b32_e32 v115, v0
	v_mov_b32_e32 v116, v0
	v_mov_b32_e32 v117, v0
	v_mov_b32_e32 v118, v0
	v_mov_b32_e32 v119, v0
	v_mov_b32_e32 v128, v0
	v_mov_b32_e32 v129, v0
	v_mov_b32_e32 v130, v0
	v_mov_b32_e32 v131, v0
	v_mov_b32_e32 v132, v0
	v_mov_b32_e32 v133, v0
	v_mov_b32_e32 v134, v0
	v_mov_b32_e32 v135, v0
	v_mov_b32_e32 v144, v0
	v_mov_b32_e32 v145, v0
	v_mov_b32_e32 v146, v0
	v_mov_b32_e32 v147, v0
	v_mov_b32_e32 v148, v0
	v_mov_b32_e32 v149, v0
	v_mov_b32_e32 v150, v0
	v_mov_b32_e32 v151, v0
	v_mov_b32_e32 v104, v0
	v_mov_b32_e32 v105, v0
	v_mov_b32_e32 v106, v0
	v_mov_b32_e32 v107, v0
	v_mov_b32_e32 v108, v0
	v_mov_b32_e32 v109, v0
	v_mov_b32_e32 v110, v0
	v_mov_b32_e32 v111, v0
	v_mov_b32_e32 v120, v0
	v_mov_b32_e32 v121, v0
	v_mov_b32_e32 v122, v0
	v_mov_b32_e32 v123, v0
	v_mov_b32_e32 v124, v0
	v_mov_b32_e32 v125, v0
	v_mov_b32_e32 v126, v0
	v_mov_b32_e32 v127, v0
	v_mov_b32_e32 v136, v0
	v_mov_b32_e32 v137, v0
	v_mov_b32_e32 v138, v0
	v_mov_b32_e32 v139, v0
	v_mov_b32_e32 v140, v0
	v_mov_b32_e32 v141, v0
	v_mov_b32_e32 v142, v0
	v_mov_b32_e32 v143, v0
	v_mov_b32_e32 v152, v0
	v_mov_b32_e32 v153, v0
	v_mov_b32_e32 v154, v0
	v_mov_b32_e32 v155, v0
	v_mov_b32_e32 v156, v0
	v_mov_b32_e32 v157, v0
	v_mov_b32_e32 v158, v0
	v_mov_b32_e32 v159, v0
	.p2align 6

.LBB0_1082:
	s_ashr_i32 s51, s50, 31
	s_lshl_b64 s[8:9], s[50:51], 19
	s_add_u32 s52, s26, s8
	s_addc_u32 s53, s27, s9
	s_and_b64 s[8:9], s[0:1], exec
	s_cselect_b32 s51, s53, s7
	s_cselect_b32 s70, s52, s6
	s_ashr_i32 s49, s48, 31
	s_lshl_b64 s[8:9], s[48:49], 19
	s_add_u32 s54, s33, s8
	s_addc_u32 s55, s41, s9
	s_and_b64 s[8:9], s[0:1], exec
	s_cselect_b32 s49, s55, s3
	s_cselect_b32 s71, s54, s2
	s_add_u32 s6, s6, 0x40080
	s_addc_u32 s7, s7, 0
	s_add_u32 s72, s2, 0x100
	v_mov_b32_e32 v0, 0
	s_addc_u32 s73, s3, 0
	s_mov_b32 s74, -2
	v_mov_b32_e32 v1, v0
	v_mov_b32_e32 v2, v0
	v_mov_b32_e32 v3, v0
	v_mov_b32_e32 v4, v0
	v_mov_b32_e32 v5, v0
	v_mov_b32_e32 v6, v0
	v_mov_b32_e32 v7, v0
	v_mov_b32_e32 v16, v0
	v_mov_b32_e32 v17, v0
	v_mov_b32_e32 v18, v0
	v_mov_b32_e32 v19, v0
	v_mov_b32_e32 v20, v0
	v_mov_b32_e32 v21, v0
	v_mov_b32_e32 v22, v0
	v_mov_b32_e32 v23, v0
	v_mov_b32_e32 v32, v0
	v_mov_b32_e32 v33, v0
	v_mov_b32_e32 v34, v0
	v_mov_b32_e32 v35, v0
	v_mov_b32_e32 v36, v0
	v_mov_b32_e32 v37, v0
	v_mov_b32_e32 v38, v0
	v_mov_b32_e32 v39, v0
	v_mov_b32_e32 v48, v0
	v_mov_b32_e32 v49, v0
	v_mov_b32_e32 v50, v0
	v_mov_b32_e32 v51, v0
	v_mov_b32_e32 v52, v0
	v_mov_b32_e32 v53, v0
	v_mov_b32_e32 v54, v0
	v_mov_b32_e32 v55, v0
	v_mov_b32_e32 v8, v0
	v_mov_b32_e32 v9, v0
	v_mov_b32_e32 v10, v0
	v_mov_b32_e32 v11, v0
	v_mov_b32_e32 v12, v0
	v_mov_b32_e32 v13, v0
	v_mov_b32_e32 v14, v0
	v_mov_b32_e32 v15, v0
	v_mov_b32_e32 v24, v0
	v_mov_b32_e32 v25, v0
	v_mov_b32_e32 v26, v0
	v_mov_b32_e32 v27, v0
	v_mov_b32_e32 v28, v0
	v_mov_b32_e32 v29, v0
	v_mov_b32_e32 v30, v0
	v_mov_b32_e32 v31, v0
	v_mov_b32_e32 v40, v0
	v_mov_b32_e32 v41, v0
	v_mov_b32_e32 v42, v0
	v_mov_b32_e32 v43, v0
	v_mov_b32_e32 v44, v0
	v_mov_b32_e32 v45, v0
	v_mov_b32_e32 v46, v0
	v_mov_b32_e32 v47, v0
	v_mov_b32_e32 v56, v0
	v_mov_b32_e32 v57, v0
	v_mov_b32_e32 v58, v0
	v_mov_b32_e32 v59, v0
	v_mov_b32_e32 v60, v0
	v_mov_b32_e32 v61, v0
	v_mov_b32_e32 v62, v0
	v_mov_b32_e32 v63, v0
	s_waitcnt vmcnt(0)
	v_mov_b32_e32 v64, v0
	v_mov_b32_e32 v65, v0
	v_mov_b32_e32 v66, v0
	v_mov_b32_e32 v67, v0
	v_mov_b32_e32 v68, v0
	v_mov_b32_e32 v69, v0
	v_mov_b32_e32 v70, v0
	v_mov_b32_e32 v71, v0
	v_mov_b32_e32 v80, v0
	v_mov_b32_e32 v81, v0
	v_mov_b32_e32 v82, v0
	v_mov_b32_e32 v83, v0
	v_mov_b32_e32 v84, v0
	v_mov_b32_e32 v85, v0
	v_mov_b32_e32 v86, v0
	v_mov_b32_e32 v87, v0
	v_mov_b32_e32 v96, v0
	v_mov_b32_e32 v97, v0
	v_mov_b32_e32 v98, v0
	v_mov_b32_e32 v99, v0
	v_mov_b32_e32 v100, v0
	v_mov_b32_e32 v101, v0
	v_mov_b32_e32 v102, v0
	v_mov_b32_e32 v103, v0
	v_mov_b32_e32 v112, v0
	v_mov_b32_e32 v113, v0
	v_mov_b32_e32 v114, v0
	v_mov_b32_e32 v115, v0
	v_mov_b32_e32 v116, v0
	v_mov_b32_e32 v117, v0
	v_mov_b32_e32 v118, v0
	v_mov_b32_e32 v119, v0
	v_mov_b32_e32 v72, v0
	v_mov_b32_e32 v73, v0
	v_mov_b32_e32 v74, v0
	v_mov_b32_e32 v75, v0
	v_mov_b32_e32 v76, v0
	v_mov_b32_e32 v77, v0
	v_mov_b32_e32 v78, v0
	v_mov_b32_e32 v79, v0
	v_mov_b32_e32 v88, v0
	v_mov_b32_e32 v89, v0
	v_mov_b32_e32 v90, v0
	v_mov_b32_e32 v91, v0
	v_mov_b32_e32 v92, v0
	v_mov_b32_e32 v93, v0
	v_mov_b32_e32 v94, v0
	v_mov_b32_e32 v95, v0
	v_mov_b32_e32 v104, v0
	v_mov_b32_e32 v105, v0
	v_mov_b32_e32 v106, v0
	v_mov_b32_e32 v107, v0
	v_mov_b32_e32 v108, v0
	v_mov_b32_e32 v109, v0
	v_mov_b32_e32 v110, v0
	v_mov_b32_e32 v111, v0
	v_mov_b32_e32 v120, v0
	v_mov_b32_e32 v121, v0
	v_mov_b32_e32 v122, v0
	v_mov_b32_e32 v123, v0
	v_mov_b32_e32 v124, v0
	v_mov_b32_e32 v125, v0
	v_mov_b32_e32 v126, v0
	v_mov_b32_e32 v127, v0
	.p2align 6

.LBB0_1155:
	s_ashr_i32 s43, s42, 31
	s_lshl_b64 s[44:45], s[42:43], 21
	s_add_u32 s44, s24, s44
	s_addc_u32 s45, s25, s45
	s_and_b64 s[46:47], s[6:7], exec
	s_cselect_b32 s43, s45, s49
	s_cselect_b32 s62, s44, s48
	s_ashr_i32 s41, s40, 31
	s_lshl_b64 s[46:47], s[40:41], 21
	s_add_u32 s46, s33, s46
	s_addc_u32 s47, s37, s47
	s_and_b64 s[50:51], s[6:7], exec
	s_cselect_b32 s41, s47, s3
	s_cselect_b32 s63, s46, s2
	s_add_u32 s48, s48, 0x100080
	s_addc_u32 s49, s49, 0
	s_add_u32 s64, s2, 0x100
	v_mov_b32_e32 v0, 0
	s_addc_u32 s65, s3, 0
	s_mov_b32 s66, -2
	v_mov_b32_e32 v1, v0
	v_mov_b32_e32 v2, v0
	v_mov_b32_e32 v3, v0
	v_mov_b32_e32 v4, v0
	v_mov_b32_e32 v5, v0
	v_mov_b32_e32 v6, v0
	v_mov_b32_e32 v7, v0
	v_mov_b32_e32 v16, v0
	v_mov_b32_e32 v17, v0
	v_mov_b32_e32 v18, v0
	v_mov_b32_e32 v19, v0
	v_mov_b32_e32 v20, v0
	v_mov_b32_e32 v21, v0
	v_mov_b32_e32 v22, v0
	v_mov_b32_e32 v23, v0
	v_mov_b32_e32 v32, v0
	v_mov_b32_e32 v33, v0
	v_mov_b32_e32 v34, v0
	v_mov_b32_e32 v35, v0
	v_mov_b32_e32 v36, v0
	v_mov_b32_e32 v37, v0
	v_mov_b32_e32 v38, v0
	v_mov_b32_e32 v39, v0
	v_mov_b32_e32 v48, v0
	v_mov_b32_e32 v49, v0
	v_mov_b32_e32 v50, v0
	v_mov_b32_e32 v51, v0
	v_mov_b32_e32 v52, v0
	v_mov_b32_e32 v53, v0
	v_mov_b32_e32 v54, v0
	v_mov_b32_e32 v55, v0
	v_mov_b32_e32 v8, v0
	v_mov_b32_e32 v9, v0
	v_mov_b32_e32 v10, v0
	v_mov_b32_e32 v11, v0
	v_mov_b32_e32 v12, v0
	v_mov_b32_e32 v13, v0
	v_mov_b32_e32 v14, v0
	v_mov_b32_e32 v15, v0
	v_mov_b32_e32 v24, v0
	v_mov_b32_e32 v25, v0
	v_mov_b32_e32 v26, v0
	v_mov_b32_e32 v27, v0
	v_mov_b32_e32 v28, v0
	v_mov_b32_e32 v29, v0
	v_mov_b32_e32 v30, v0
	v_mov_b32_e32 v31, v0
	v_mov_b32_e32 v40, v0
	v_mov_b32_e32 v41, v0
	v_mov_b32_e32 v42, v0
	v_mov_b32_e32 v43, v0
	v_mov_b32_e32 v44, v0
	v_mov_b32_e32 v45, v0
	v_mov_b32_e32 v46, v0
	v_mov_b32_e32 v47, v0
	v_mov_b32_e32 v56, v0
	v_mov_b32_e32 v57, v0
	v_mov_b32_e32 v58, v0
	v_mov_b32_e32 v59, v0
	v_mov_b32_e32 v60, v0
	v_mov_b32_e32 v61, v0
	v_mov_b32_e32 v62, v0
	v_mov_b32_e32 v63, v0
	s_waitcnt vmcnt(0)
	v_mov_b32_e32 v80, v0
	v_mov_b32_e32 v81, v0
	v_mov_b32_e32 v82, v0
	v_mov_b32_e32 v83, v0
	v_mov_b32_e32 v84, v0
	v_mov_b32_e32 v85, v0
	v_mov_b32_e32 v86, v0
	v_mov_b32_e32 v87, v0
	v_mov_b32_e32 v112, v0
	v_mov_b32_e32 v113, v0
	v_mov_b32_e32 v114, v0
	v_mov_b32_e32 v115, v0
	v_mov_b32_e32 v116, v0
	v_mov_b32_e32 v117, v0
	v_mov_b32_e32 v118, v0
	v_mov_b32_e32 v119, v0
	v_mov_b32_e32 v128, v0
	v_mov_b32_e32 v129, v0
	v_mov_b32_e32 v130, v0
	v_mov_b32_e32 v131, v0
	v_mov_b32_e32 v132, v0
	v_mov_b32_e32 v133, v0
	v_mov_b32_e32 v134, v0
	v_mov_b32_e32 v135, v0
	v_mov_b32_e32 v144, v0
	v_mov_b32_e32 v145, v0
	v_mov_b32_e32 v146, v0
	v_mov_b32_e32 v147, v0
	v_mov_b32_e32 v148, v0
	v_mov_b32_e32 v149, v0
	v_mov_b32_e32 v150, v0
	v_mov_b32_e32 v151, v0
	v_mov_b32_e32 v104, v0
	v_mov_b32_e32 v105, v0
	v_mov_b32_e32 v106, v0
	v_mov_b32_e32 v107, v0
	v_mov_b32_e32 v108, v0
	v_mov_b32_e32 v109, v0
	v_mov_b32_e32 v110, v0
	v_mov_b32_e32 v111, v0
	v_mov_b32_e32 v120, v0
	v_mov_b32_e32 v121, v0
	v_mov_b32_e32 v122, v0
	v_mov_b32_e32 v123, v0
	v_mov_b32_e32 v124, v0
	v_mov_b32_e32 v125, v0
	v_mov_b32_e32 v126, v0
	v_mov_b32_e32 v127, v0
	v_mov_b32_e32 v136, v0
	v_mov_b32_e32 v137, v0
	v_mov_b32_e32 v138, v0
	v_mov_b32_e32 v139, v0
	v_mov_b32_e32 v140, v0
	v_mov_b32_e32 v141, v0
	v_mov_b32_e32 v142, v0
	v_mov_b32_e32 v143, v0
	v_mov_b32_e32 v152, v0
	v_mov_b32_e32 v153, v0
	v_mov_b32_e32 v154, v0
	v_mov_b32_e32 v155, v0
	v_mov_b32_e32 v156, v0
	v_mov_b32_e32 v157, v0
	v_mov_b32_e32 v158, v0
	v_mov_b32_e32 v159, v0
	.p2align 6
